# baseline (speedup 1.0000x reference)
;   __device__ __forceinline__ u16* hbuf() const { return (u16*)(ws + 57 * MB); }
;   __device__ __forceinline__ u16* proj() const { return (u16*)(ws + 185 * MB); }
; __device__ __forceinline__ float bflo(unsigned u) { return __uint_as_float(u << 16); }
; __device__ __forceinline__ float bfhi(unsigned u) { return __uint_as_float(u & 0xffff0000u); }
; #define LDS_FENCE() asm volatile("s_waitcnt lgkmcnt(0)" ::: "memory")
; template <int EPI> ...
;     ...
;           for (int mm = 0; mm < 4; ++mm)
; #pragma unroll
;             for (int n = 0; n < 4; ++n) {
;               const f32x4 v = acc[h * 4 + mm][n];
;               u32x2 o = {pack2(v[0], v[1]), pack2(v[2], v[3])};
;               *(u32x2*)(wst + (mm * 16 + fr) * 128 + (((n * 2 + (fq >> 1)) ^ wswz) << 4) + (fq & 1) * 8) = o;
;             }
;           LDS_FENCE();
; #pragma unroll
;           for (int ib = 0; ib < 2; ++ib) {
;             u32x4 g0v[4], g1v[4], pv[4];
; #pragma unroll
;             for (int i = 0; i < 4; ++i) {
;               const long gr = rbase + h * 64 + (ib * 4 + i) * 8;
;               g0v[i] = *(const u32x4*)(p.proj() + gr * INW + 2304 + cbase);
;               g1v[i] = *(const u32x4*)(p.proj() + gr * INW + 3328 + cbase);
;               pv[i] = *(const u32x4*)(p.hbuf() + gr * DM + cbase);
;             }
; #pragma unroll
;             for (int i = 0; i < 4; ++i) {
;               const long gr = rbase + h * 64 + (ib * 4 + i) * 8;
;               const u32x4 a = *(const u32x4*)(wst + ((ib * 4 + i) * 8 + (lane >> 3)) * 128 + (((lane & 7) ^ rswz) << 4));
;               u32x4 o;
; #pragma unroll
;               for (int c = 0; c < 4; ++c) {
;                 const float lo = bflo(a[c]) * bflo(g1v[i][c]) + bflo(pv[i][c]) * (bflo(g0v[i][c]) - bflo(g1v[i][c]));
;                 const float hi = bfhi(a[c]) * bfhi(g1v[i][c]) + bfhi(pv[i][c]) * (bfhi(g0v[i][c]) - bfhi(g1v[i][c]));
;                 o[c] = pack2(lo, hi);
;               }
;               *(u32x4*)(p.hbuf() + gr * DM + cbase) = o;
.LBB0_520:
	s_or_b64 exec, exec, s[14:15]
	v_mov_b32_e32 v142, v3
	v_cvt_pk_bf16_f32 v141, v126, v127
	v_and_b32_e32 v145, 7, v142
	v_lshlrev_b32_e32 v139, 7, v142
	v_and_b32_e32 v138, 0xc0, v142
	v_lshlrev_b32_e32 v140, 3, v145
	v_and_b32_e32 v136, 0xffffe000, v139
	v_or3_b32 v138, v140, v138, s12
	v_lshrrev_b32_e32 v140, 1, v142
	v_add_u32_e32 v143, 0x10000, v136
	v_and_b32_e32 v139, 0x780, v139
	v_bfe_u32 v147, v142, 5, 1
	v_and_b32_e32 v140, 8, v140
	v_or3_b32 v148, v143, v139, v140
	v_cvt_pk_bf16_f32 v126, v116, v117
	v_bitop3_b32 v116, v147, v145, 2 bitop3:0x36
	v_ashrrev_i32_e32 v136, 1, v142
	v_lshl_or_b32 v117, v116, 4, v148
	v_bitop3_b32 v116, v147, v145, 4 bitop3:0x36
	v_cvt_pk_bf16_f32 v80, v80, v81
	v_cvt_pk_bf16_f32 v81, v82, v83
	v_cvt_pk_bf16_f32 v72, v72, v73
	v_cvt_pk_bf16_f32 v73, v74, v75
	v_and_b32_e32 v136, 0xffffff80, v136
	v_cvt_pk_bf16_f32 v127, v118, v119
	v_lshl_or_b32 v118, v116, 4, v148
	v_bitop3_b32 v116, v147, v145, 6 bitop3:0x36
	v_cvt_pk_bf16_f32 v82, v108, v109
	v_cvt_pk_bf16_f32 v83, v110, v111
	ds_write2st64_b64 v117, v[80:81], v[72:73] offset0:8 offset1:12
	v_cvt_pk_bf16_f32 v72, v92, v93
	v_cvt_pk_bf16_f32 v73, v94, v95
	v_add_u32_e32 v136, s51, v136
	v_bfe_u32 v146, v142, 3, 3
	v_lshl_or_b32 v119, v116, 4, v148
	v_cvt_pk_bf16_f32 v84, v84, v85
	v_cvt_pk_bf16_f32 v85, v86, v87
	v_cvt_pk_bf16_f32 v86, v104, v105
	v_cvt_pk_bf16_f32 v87, v106, v107
	ds_write2st64_b64 v118, v[82:83], v[72:73] offset0:8 offset1:12
	v_cvt_pk_bf16_f32 v72, v88, v89
	v_cvt_pk_bf16_f32 v73, v90, v91
	v_or_b32_e32 v136, v136, v146
	v_ashrrev_i32_e32 v139, 31, v138
	v_cvt_pk_bf16_f32 v96, v96, v97
	v_cvt_pk_bf16_f32 v97, v98, v99
	ds_write2st64_b64 v119, v[86:87], v[72:73] offset0:8 offset1:12
	v_mov_b64_e32 v[72:73], s[38:39]
	v_cvt_pk_bf16_f32 v140, v124, v125
	v_bitop3_b32 v124, v147, v142, 7 bitop3:0x78
	v_cvt_pk_bf16_f32 v132, v132, v133
	v_cvt_pk_bf16_f32 v133, v134, v135
	ds_write2st64_b64 v117, v[126:127], v[96:97] offset1:4
	v_cvt_pk_bf16_f32 v96, v120, v121
	v_cvt_pk_bf16_f32 v97, v122, v123
	v_lshlrev_b64 v[108:109], 1, v[138:139]
	v_mad_i64_i32 v[72:73], s[12:13], v136, s88, v[72:73]
	v_ashrrev_i32_e32 v137, 31, v136
	v_lshl_or_b32 v124, v124, 4, v148
	v_cvt_pk_bf16_f32 v128, v128, v129
	v_cvt_pk_bf16_f32 v129, v130, v131
	v_cvt_pk_bf16_f32 v100, v100, v101
	v_cvt_pk_bf16_f32 v101, v102, v103
	ds_write2st64_b64 v118, v[132:133], v[96:97] offset1:4
	v_cvt_pk_bf16_f32 v96, v112, v113
	v_cvt_pk_bf16_f32 v97, v114, v115
	v_cvt_pk_bf16_f32 v76, v76, v77
	v_cvt_pk_bf16_f32 v77, v78, v79
	v_lshl_add_u64 v[114:115], v[72:73], 0, v[108:109]
	s_movk_i32 s12, 0x1000
	ds_write2st64_b64 v124, v[140:141], v[100:101] offset1:4
	ds_write2st64_b64 v119, v[128:129], v[96:97] offset1:4
	ds_write2st64_b64 v124, v[84:85], v[76:77] offset0:8 offset1:12
	v_lshl_add_u64 v[112:113], s[40:41], 0, v[108:109]
	v_add_co_u32_e32 v72, vcc, s12, v114
	v_lshlrev_b64 v[110:111], 11, v[136:137]
	s_waitcnt lgkmcnt(0)
	s_nop 0
	v_addc_co_u32_e32 v73, vcc, 0, v115, vcc
	v_lshl_add_u64 v[74:75], v[112:113], 0, v[110:111]
	global_load_dwordx4 v[120:123], v[72:73], off offset:2560 nt
	global_load_dwordx4 v[126:129], v[74:75], off nt
	global_load_dwordx4 v[130:133], v[72:73], off offset:512 nt
	v_bitop3_b32 v72, v146, v142, 7 bitop3:0x78
	s_mov_b32 s12, 0x12000
	v_lshlrev_b32_e32 v80, 4, v72
	v_add_co_u32_e32 v72, vcc, s12, v114
	s_mov_b32 s12, 0x23000
	s_nop 0
	v_addc_co_u32_e32 v73, vcc, 0, v115, vcc
	global_load_dwordx4 v[96:99], v[72:73], off offset:512 nt
	global_load_dwordx4 v[100:103], v[72:73], off offset:2560 nt
	v_or_b32_e32 v72, 0x4000, v110
	v_mov_b32_e32 v73, v111
	v_lshl_add_u64 v[72:73], v[112:113], 0, v[72:73]
	global_load_dwordx4 v[104:107], v[72:73], off nt
	v_add_co_u32_e32 v72, vcc, s12, v114
	v_lshlrev_b32_e32 v81, 7, v146
	s_nop 0
	v_addc_co_u32_e32 v73, vcc, 0, v115, vcc
	global_load_dwordx4 v[84:87], v[72:73], off offset:512 nt
	global_load_dwordx4 v[88:91], v[72:73], off offset:2560 nt
	v_or_b32_e32 v72, 0x8000, v110
	v_mov_b32_e32 v73, v111
	v_lshl_add_u64 v[72:73], v[112:113], 0, v[72:73]
	global_load_dwordx4 v[92:95], v[72:73], off nt
	v_add_co_u32_e32 v76, vcc, s36, v114
	v_or3_b32 v116, v143, v80, v81
	s_nop 0
	v_addc_co_u32_e32 v77, vcc, 0, v115, vcc
	v_or_b32_e32 v80, 0xc000, v110
	v_mov_b32_e32 v81, v111
	global_load_dwordx4 v[72:75], v[76:77], off offset:512 nt
	s_nop 0
	global_load_dwordx4 v[76:79], v[76:77], off offset:2560 nt
	v_lshl_add_u64 v[80:81], v[112:113], 0, v[80:81]
	global_load_dwordx4 v[80:83], v[80:81], off nt
	ds_read_b128 v[134:137], v116
	v_readlane_b32 s12, v254, 42
	v_readlane_b32 s13, v254, 43
	s_waitcnt lgkmcnt(0)
	v_lshlrev_b32_e32 v138, 16, v134
	v_and_b32_e32 v139, 0xffff0000, v134
	v_lshlrev_b32_e32 v134, 16, v135
	v_and_b32_e32 v135, 0xffff0000, v135
	s_waitcnt vmcnt(0)
;   __device__ __forceinline__ u16* hbuf() const { return (u16*)(ws + 57 * MB); }
; __device__ __forceinline__ float bflo(unsigned u) { return __uint_as_float(u << 16); }
; __device__ __forceinline__ float bfhi(unsigned u) { return __uint_as_float(u & 0xffff0000u); }
; template <int EPI> ...
;     ...
; #pragma unroll
;             for (int i = 0; i < 4; ++i) {
;               const long gr = rbase + h * 64 + (ib * 4 + i) * 8;
;               const u32x4 a = *(const u32x4*)(wst + ((ib * 4 + i) * 8 + (lane >> 3)) * 128 + (((lane & 7) ^ rswz) << 4));
;               u32x4 o;
; #pragma unroll
;               for (int c = 0; c < 4; ++c) {
;                 const float lo = bflo(a[c]) * bflo(g1v[i][c]) + bflo(pv[i][c]) * (bflo(g0v[i][c]) - bflo(g1v[i][c]));
;                 const float hi = bfhi(a[c]) * bfhi(g1v[i][c]) + bfhi(pv[i][c]) * (bfhi(g0v[i][c]) - bfhi(g1v[i][c]));
;                 o[c] = pack2(lo, hi);
;               }
;               *(u32x4*)(p.hbuf() + gr * DM + cbase) = o;
	v_lshlrev_b32_e32 v140, 16, v120
	v_and_b32_e32 v141, 0xffff0000, v120
	v_lshlrev_b32_e32 v146, 16, v130
	v_and_b32_e32 v147, 0xffff0000, v130
	v_pk_mul_f32 v[138:139], v[140:141], v[138:139]
	v_lshlrev_b32_e32 v142, 16, v126
	v_and_b32_e32 v143, 0xffff0000, v126
	v_pk_add_f32 v[140:141], v[146:147], v[140:141] neg_lo:[0,1] neg_hi:[0,1]
	v_lshlrev_b32_e32 v130, 16, v131
	v_pk_fma_f32 v[138:139], v[140:141], v[142:143], v[138:139]
	v_and_b32_e32 v131, 0xffff0000, v131
	v_cvt_pk_bf16_f32 v120, v138, v139
	v_lshlrev_b32_e32 v138, 16, v121
	v_and_b32_e32 v139, 0xffff0000, v121
	v_pk_mul_f32 v[134:135], v[138:139], v[134:135]
	v_lshlrev_b32_e32 v126, 16, v127
	v_and_b32_e32 v127, 0xffff0000, v127
	v_pk_add_f32 v[130:131], v[130:131], v[138:139] neg_lo:[0,1] neg_hi:[0,1]
	v_lshlrev_b32_e32 v138, 16, v132
	v_pk_fma_f32 v[126:127], v[130:131], v[126:127], v[134:135]
	v_lshlrev_b32_e32 v130, 16, v122
	v_cvt_pk_bf16_f32 v121, v126, v127
	v_lshlrev_b32_e32 v126, 16, v136
	v_and_b32_e32 v127, 0xffff0000, v136
	v_and_b32_e32 v131, 0xffff0000, v122
	v_and_b32_e32 v139, 0xffff0000, v132
	v_pk_mul_f32 v[126:127], v[130:131], v[126:127]
	v_lshlrev_b32_e32 v134, 16, v128
	v_and_b32_e32 v135, 0xffff0000, v128
	v_pk_add_f32 v[130:131], v[138:139], v[130:131] neg_lo:[0,1] neg_hi:[0,1]
	v_lshlrev_b32_e32 v132, 16, v133
	v_pk_fma_f32 v[126:127], v[130:131], v[134:135], v[126:127]
	v_lshlrev_b32_e32 v130, 16, v123
	v_cvt_pk_bf16_f32 v122, v126, v127
	v_lshlrev_b32_e32 v126, 16, v137
	v_and_b32_e32 v127, 0xffff0000, v137
	v_and_b32_e32 v131, 0xffff0000, v123
	v_and_b32_e32 v133, 0xffff0000, v133
	v_pk_mul_f32 v[126:127], v[130:131], v[126:127]
	v_lshlrev_b32_e32 v128, 16, v129
	v_and_b32_e32 v129, 0xffff0000, v129
	v_pk_add_f32 v[130:131], v[132:133], v[130:131] neg_lo:[0,1] neg_hi:[0,1]
	v_lshlrev_b32_e32 v132, 16, v96
	v_pk_fma_f32 v[130:131], v[130:131], v[128:129], v[126:127]
	ds_read_b128 v[126:129], v116 offset:1024
	v_cvt_pk_bf16_f32 v123, v130, v131
	v_lshl_add_u64 v[130:131], s[40:41], 0, v[110:111]
	v_lshl_add_u64 v[130:131], v[130:131], 0, v[108:109]
	global_store_dwordx4 v[130:131], v[120:123], off
	v_and_b32_e32 v133, 0xffff0000, v96
	v_lshlrev_b32_e32 v130, 16, v104
	s_waitcnt lgkmcnt(0)
	v_lshlrev_b32_e32 v120, 16, v126
	v_and_b32_e32 v121, 0xffff0000, v126
	v_lshlrev_b32_e32 v122, 16, v100
	v_and_b32_e32 v123, 0xffff0000, v100
	v_pk_mul_f32 v[120:121], v[122:123], v[120:121]
	v_and_b32_e32 v131, 0xffff0000, v104
	v_pk_add_f32 v[122:123], v[132:133], v[122:123] neg_lo:[0,1] neg_hi:[0,1]
	v_lshlrev_b32_e32 v100, 16, v101
	v_pk_fma_f32 v[120:121], v[122:123], v[130:131], v[120:121]
	v_and_b32_e32 v101, 0xffff0000, v101
	v_cvt_pk_bf16_f32 v96, v120, v121
	v_lshlrev_b32_e32 v120, 16, v127
	v_and_b32_e32 v121, 0xffff0000, v127
	v_lshlrev_b32_e32 v122, 16, v97
	v_and_b32_e32 v123, 0xffff0000, v97
	v_pk_mul_f32 v[120:121], v[100:101], v[120:121]
	v_lshlrev_b32_e32 v104, 16, v105
	v_and_b32_e32 v105, 0xffff0000, v105
	v_pk_add_f32 v[100:101], v[122:123], v[100:101] neg_lo:[0,1] neg_hi:[0,1]
	v_lshlrev_b32_e32 v122, 16, v98
	v_pk_fma_f32 v[100:101], v[100:101], v[104:105], v[120:121]
	v_lshlrev_b32_e32 v104, 16, v102
	v_cvt_pk_bf16_f32 v97, v100, v101
	v_lshlrev_b32_e32 v100, 16, v128
	v_and_b32_e32 v101, 0xffff0000, v128
	v_and_b32_e32 v105, 0xffff0000, v102
	v_and_b32_e32 v123, 0xffff0000, v98
	v_pk_mul_f32 v[100:101], v[104:105], v[100:101]
	v_lshlrev_b32_e32 v120, 16, v106
	v_and_b32_e32 v121, 0xffff0000, v106
	v_pk_add_f32 v[104:105], v[122:123], v[104:105] neg_lo:[0,1] neg_hi:[0,1]
	v_lshlrev_b32_e32 v102, 16, v103
	v_pk_fma_f32 v[100:101], v[104:105], v[120:121], v[100:101]
	v_and_b32_e32 v103, 0xffff0000, v103
	v_cvt_pk_bf16_f32 v98, v100, v101
	v_lshlrev_b32_e32 v100, 16, v129
	v_and_b32_e32 v101, 0xffff0000, v129
	v_lshlrev_b32_e32 v104, 16, v107
	v_and_b32_e32 v105, 0xffff0000, v107
	v_lshlrev_b32_e32 v106, 16, v99
	v_and_b32_e32 v107, 0xffff0000, v99
	v_pk_mul_f32 v[100:101], v[102:103], v[100:101]
	v_pk_add_f32 v[102:103], v[106:107], v[102:103] neg_lo:[0,1] neg_hi:[0,1]
	v_lshlrev_b32_e32 v106, 16, v84
	v_pk_fma_f32 v[104:105], v[102:103], v[104:105], v[100:101]
	ds_read_b128 v[100:103], v116 offset:2048
	v_cvt_pk_bf16_f32 v99, v104, v105
	v_lshl_add_u64 v[104:105], s[12:13], 0, v[110:111]
	v_lshl_add_u64 v[104:105], v[104:105], 0, v[108:109]
	global_store_dwordx4 v[104:105], v[96:99], off
	v_and_b32_e32 v107, 0xffff0000, v84
	v_lshlrev_b32_e32 v104, 16, v92
	s_waitcnt lgkmcnt(0)
	v_lshlrev_b32_e32 v96, 16, v100
	v_and_b32_e32 v97, 0xffff0000, v100
	v_lshlrev_b32_e32 v98, 16, v88
	v_and_b32_e32 v99, 0xffff0000, v88
	v_pk_mul_f32 v[96:97], v[98:99], v[96:97]
	v_and_b32_e32 v105, 0xffff0000, v92
	v_pk_add_f32 v[98:99], v[106:107], v[98:99] neg_lo:[0,1] neg_hi:[0,1]
	v_lshlrev_b32_e32 v88, 16, v89
	v_pk_fma_f32 v[96:97], v[98:99], v[104:105], v[96:97]
	v_and_b32_e32 v89, 0xffff0000, v89
	v_cvt_pk_bf16_f32 v84, v96, v97
	v_lshlrev_b32_e32 v96, 16, v101
	v_and_b32_e32 v97, 0xffff0000, v101
	v_lshlrev_b32_e32 v98, 16, v85
	v_and_b32_e32 v99, 0xffff0000, v85
	v_pk_mul_f32 v[96:97], v[88:89], v[96:97]
	v_lshlrev_b32_e32 v92, 16, v93
	v_and_b32_e32 v93, 0xffff0000, v93
	v_pk_add_f32 v[88:89], v[98:99], v[88:89] neg_lo:[0,1] neg_hi:[0,1]
	v_lshlrev_b32_e32 v98, 16, v86
	v_pk_fma_f32 v[88:89], v[88:89], v[92:93], v[96:97]
	v_lshlrev_b32_e32 v92, 16, v90
	v_cvt_pk_bf16_f32 v85, v88, v89
	v_lshlrev_b32_e32 v88, 16, v102
	v_and_b32_e32 v89, 0xffff0000, v102
	v_and_b32_e32 v93, 0xffff0000, v90
	v_and_b32_e32 v99, 0xffff0000, v86
	v_pk_mul_f32 v[88:89], v[92:93], v[88:89]
	v_lshlrev_b32_e32 v96, 16, v94
	v_and_b32_e32 v97, 0xffff0000, v94
	v_pk_add_f32 v[92:93], v[98:99], v[92:93] neg_lo:[0,1] neg_hi:[0,1]
	v_lshlrev_b32_e32 v90, 16, v91
	v_pk_fma_f32 v[88:89], v[92:93], v[96:97], v[88:89]
	v_and_b32_e32 v91, 0xffff0000, v91
	v_cvt_pk_bf16_f32 v86, v88, v89
	v_lshlrev_b32_e32 v88, 16, v103
	v_and_b32_e32 v89, 0xffff0000, v103
	v_lshlrev_b32_e32 v92, 16, v95
	v_and_b32_e32 v93, 0xffff0000, v95
	v_lshlrev_b32_e32 v94, 16, v87
	v_and_b32_e32 v95, 0xffff0000, v87
	v_pk_mul_f32 v[88:89], v[90:91], v[88:89]
	v_pk_add_f32 v[90:91], v[94:95], v[90:91] neg_lo:[0,1] neg_hi:[0,1]
	v_readlane_b32 s12, v254, 44
	v_pk_fma_f32 v[92:93], v[90:91], v[92:93], v[88:89]
	ds_read_b128 v[88:91], v116 offset:3072
	v_readlane_b32 s13, v254, 45
	v_cvt_pk_bf16_f32 v87, v92, v93
	v_lshlrev_b32_e32 v94, 16, v72
	v_lshl_add_u64 v[92:93], s[12:13], 0, v[110:111]
	v_lshl_add_u64 v[92:93], v[92:93], 0, v[108:109]
	global_store_dwordx4 v[92:93], v[84:87], off
	v_and_b32_e32 v95, 0xffff0000, v72
	v_lshlrev_b32_e32 v92, 16, v80
	s_waitcnt lgkmcnt(0)
;   __device__ __forceinline__ u16* hbuf() const { return (u16*)(ws + 57 * MB); }
;   __device__ __forceinline__ u16* proj() const { return (u16*)(ws + 185 * MB); }
; __device__ __forceinline__ float bflo(unsigned u) { return __uint_as_float(u << 16); }
; __device__ __forceinline__ float bfhi(unsigned u) { return __uint_as_float(u & 0xffff0000u); }
; template <int EPI> ...
;     ...
;           for (int ib = 0; ib < 2; ++ib) {
;             u32x4 g0v[4], g1v[4], pv[4];
; #pragma unroll
;             for (int i = 0; i < 4; ++i) {
;               const long gr = rbase + h * 64 + (ib * 4 + i) * 8;
;               g0v[i] = *(const u32x4*)(p.proj() + gr * INW + 2304 + cbase);
;               g1v[i] = *(const u32x4*)(p.proj() + gr * INW + 3328 + cbase);
;               pv[i] = *(const u32x4*)(p.hbuf() + gr * DM + cbase);
;             }
; #pragma unroll
;             for (int i = 0; i < 4; ++i) {
;               const long gr = rbase + h * 64 + (ib * 4 + i) * 8;
;               const u32x4 a = *(const u32x4*)(wst + ((ib * 4 + i) * 8 + (lane >> 3)) * 128 + (((lane & 7) ^ rswz) << 4));
;               u32x4 o;
; #pragma unroll
;               for (int c = 0; c < 4; ++c) {
;                 const float lo = bflo(a[c]) * bflo(g1v[i][c]) + bflo(pv[i][c]) * (bflo(g0v[i][c]) - bflo(g1v[i][c]));
;                 const float hi = bfhi(a[c]) * bfhi(g1v[i][c]) + bfhi(pv[i][c]) * (bfhi(g0v[i][c]) - bfhi(g1v[i][c]));
;                 o[c] = pack2(lo, hi);
;               }
;               *(u32x4*)(p.hbuf() + gr * DM + cbase) = o;
	v_lshlrev_b32_e32 v84, 16, v88
	v_and_b32_e32 v85, 0xffff0000, v88
	v_lshlrev_b32_e32 v86, 16, v76
	v_and_b32_e32 v87, 0xffff0000, v76
	v_pk_mul_f32 v[84:85], v[86:87], v[84:85]
	v_and_b32_e32 v93, 0xffff0000, v80
	v_pk_add_f32 v[86:87], v[94:95], v[86:87] neg_lo:[0,1] neg_hi:[0,1]
	v_lshlrev_b32_e32 v76, 16, v77
	v_pk_fma_f32 v[84:85], v[86:87], v[92:93], v[84:85]
	v_and_b32_e32 v77, 0xffff0000, v77
	v_cvt_pk_bf16_f32 v72, v84, v85
	v_lshlrev_b32_e32 v84, 16, v89
	v_and_b32_e32 v85, 0xffff0000, v89
	v_lshlrev_b32_e32 v86, 16, v73
	v_and_b32_e32 v87, 0xffff0000, v73
	v_pk_mul_f32 v[84:85], v[76:77], v[84:85]
	v_lshlrev_b32_e32 v80, 16, v81
	v_and_b32_e32 v81, 0xffff0000, v81
	v_pk_add_f32 v[76:77], v[86:87], v[76:77] neg_lo:[0,1] neg_hi:[0,1]
	v_lshlrev_b32_e32 v86, 16, v74
	v_pk_fma_f32 v[76:77], v[76:77], v[80:81], v[84:85]
	v_lshlrev_b32_e32 v80, 16, v78
	v_cvt_pk_bf16_f32 v73, v76, v77
	v_lshlrev_b32_e32 v76, 16, v90
	v_and_b32_e32 v77, 0xffff0000, v90
	v_and_b32_e32 v81, 0xffff0000, v78
	v_and_b32_e32 v87, 0xffff0000, v74
	v_pk_mul_f32 v[76:77], v[80:81], v[76:77]
	v_lshlrev_b32_e32 v84, 16, v82
	v_and_b32_e32 v85, 0xffff0000, v82
	v_pk_add_f32 v[80:81], v[86:87], v[80:81] neg_lo:[0,1] neg_hi:[0,1]
	v_lshlrev_b32_e32 v78, 16, v79
	v_pk_fma_f32 v[76:77], v[80:81], v[84:85], v[76:77]
	v_and_b32_e32 v79, 0xffff0000, v79
	v_cvt_pk_bf16_f32 v74, v76, v77
	v_lshlrev_b32_e32 v76, 16, v91
	v_and_b32_e32 v77, 0xffff0000, v91
	v_lshlrev_b32_e32 v80, 16, v83
	v_and_b32_e32 v81, 0xffff0000, v83
	v_lshlrev_b32_e32 v82, 16, v75
	v_and_b32_e32 v83, 0xffff0000, v75
	v_pk_mul_f32 v[76:77], v[78:79], v[76:77]
	v_pk_add_f32 v[78:79], v[82:83], v[78:79] neg_lo:[0,1] neg_hi:[0,1]
	v_readlane_b32 s12, v254, 46
	v_pk_fma_f32 v[76:77], v[78:79], v[80:81], v[76:77]
	v_readlane_b32 s13, v254, 47
	v_cvt_pk_bf16_f32 v75, v76, v77
	s_nop 0
	v_lshl_add_u64 v[76:77], s[12:13], 0, v[110:111]
	v_lshl_add_u64 v[76:77], v[76:77], 0, v[108:109]
	global_store_dwordx4 v[76:77], v[72:75], off
	s_mov_b32 s12, 0x45000
	s_nop 0
	v_add_co_u32_e32 v72, vcc, s12, v114
	s_mov_b32 s12, 0x56000
	s_nop 0
	v_addc_co_u32_e32 v73, vcc, 0, v115, vcc
	global_load_dwordx4 v[120:123], v[72:73], off offset:512 nt
	global_load_dwordx4 v[126:129], v[72:73], off offset:2560 nt
	v_or_b32_e32 v72, 0x10000, v110
	v_mov_b32_e32 v73, v111
	v_lshl_add_u64 v[72:73], v[112:113], 0, v[72:73]
	global_load_dwordx4 v[130:133], v[72:73], off nt
	v_add_co_u32_e32 v72, vcc, s12, v114
	s_mov_b32 s12, 0x67000
	s_nop 0
	v_addc_co_u32_e32 v73, vcc, 0, v115, vcc
	global_load_dwordx4 v[96:99], v[72:73], off offset:512 nt
	global_load_dwordx4 v[100:103], v[72:73], off offset:2560 nt
	v_or_b32_e32 v72, 0x14000, v110
	v_mov_b32_e32 v73, v111
	v_lshl_add_u64 v[72:73], v[112:113], 0, v[72:73]
	global_load_dwordx4 v[104:107], v[72:73], off nt
	v_add_co_u32_e32 v72, vcc, s12, v114
	s_mov_b32 s12, 0x78000
	s_nop 0
	v_addc_co_u32_e32 v73, vcc, 0, v115, vcc
	global_load_dwordx4 v[84:87], v[72:73], off offset:512 nt
	global_load_dwordx4 v[88:91], v[72:73], off offset:2560 nt
	v_or_b32_e32 v72, 0x18000, v110
	v_mov_b32_e32 v73, v111
	v_lshl_add_u64 v[72:73], v[112:113], 0, v[72:73]
	global_load_dwordx4 v[92:95], v[72:73], off nt
	v_add_co_u32_e32 v76, vcc, s12, v114
	v_or_b32_e32 v80, 0x1c000, v110
	s_nop 0
	v_addc_co_u32_e32 v77, vcc, 0, v115, vcc
	v_mov_b32_e32 v81, v111
	global_load_dwordx4 v[72:75], v[76:77], off offset:512 nt
	s_nop 0
	global_load_dwordx4 v[76:79], v[76:77], off offset:2560 nt
	v_lshl_add_u64 v[80:81], v[112:113], 0, v[80:81]
	global_load_dwordx4 v[80:83], v[80:81], off nt
	ds_read_b128 v[134:137], v116 offset:4096
	v_readlane_b32 s12, v254, 48
	v_readlane_b32 s13, v254, 49
	s_waitcnt lgkmcnt(0)
	v_lshlrev_b32_e32 v138, 16, v134
	v_and_b32_e32 v139, 0xffff0000, v134
	v_lshlrev_b32_e32 v134, 16, v135
	v_and_b32_e32 v135, 0xffff0000, v135
	s_waitcnt vmcnt(11)
	v_lshlrev_b32_e32 v146, 16, v120
	s_waitcnt vmcnt(10)
	v_lshlrev_b32_e32 v140, 16, v126
	v_and_b32_e32 v141, 0xffff0000, v126
	v_and_b32_e32 v147, 0xffff0000, v120
	v_pk_mul_f32 v[138:139], v[140:141], v[138:139]
	s_waitcnt vmcnt(9)
	v_lshlrev_b32_e32 v142, 16, v130
	v_and_b32_e32 v143, 0xffff0000, v130
	v_pk_add_f32 v[140:141], v[146:147], v[140:141] neg_lo:[0,1] neg_hi:[0,1]
	v_lshlrev_b32_e32 v126, 16, v127
	v_pk_fma_f32 v[138:139], v[140:141], v[142:143], v[138:139]
	v_and_b32_e32 v127, 0xffff0000, v127
	v_cvt_pk_bf16_f32 v120, v138, v139
	v_lshlrev_b32_e32 v138, 16, v121
	v_and_b32_e32 v139, 0xffff0000, v121
	v_pk_mul_f32 v[134:135], v[126:127], v[134:135]
	v_lshlrev_b32_e32 v130, 16, v131
	v_and_b32_e32 v131, 0xffff0000, v131
	v_pk_add_f32 v[126:127], v[138:139], v[126:127] neg_lo:[0,1] neg_hi:[0,1]
	v_lshlrev_b32_e32 v138, 16, v122
	v_pk_fma_f32 v[126:127], v[126:127], v[130:131], v[134:135]
	v_lshlrev_b32_e32 v130, 16, v128
	v_cvt_pk_bf16_f32 v121, v126, v127
	v_lshlrev_b32_e32 v126, 16, v136
	v_and_b32_e32 v127, 0xffff0000, v136
	v_and_b32_e32 v131, 0xffff0000, v128
	v_and_b32_e32 v139, 0xffff0000, v122
	v_pk_mul_f32 v[126:127], v[130:131], v[126:127]
	v_lshlrev_b32_e32 v134, 16, v132
	v_and_b32_e32 v135, 0xffff0000, v132
	v_pk_add_f32 v[130:131], v[138:139], v[130:131] neg_lo:[0,1] neg_hi:[0,1]
	v_lshlrev_b32_e32 v128, 16, v129
	v_pk_fma_f32 v[126:127], v[130:131], v[134:135], v[126:127]
	v_and_b32_e32 v129, 0xffff0000, v129
	v_cvt_pk_bf16_f32 v122, v126, v127
	v_lshlrev_b32_e32 v126, 16, v137
	v_and_b32_e32 v127, 0xffff0000, v137
	v_lshlrev_b32_e32 v130, 16, v133
	v_and_b32_e32 v131, 0xffff0000, v133
	v_lshlrev_b32_e32 v132, 16, v123
	v_and_b32_e32 v133, 0xffff0000, v123
	v_pk_mul_f32 v[126:127], v[128:129], v[126:127]
	v_pk_add_f32 v[128:129], v[132:133], v[128:129] neg_lo:[0,1] neg_hi:[0,1]
	s_waitcnt vmcnt(8)
;   __device__ __forceinline__ u16* hbuf() const { return (u16*)(ws + 57 * MB); }
; __device__ __forceinline__ float bflo(unsigned u) { return __uint_as_float(u << 16); }
; __device__ __forceinline__ float bfhi(unsigned u) { return __uint_as_float(u & 0xffff0000u); }
; template <int EPI> ...
;     ...
; #pragma unroll
;             for (int i = 0; i < 4; ++i) {
;               const long gr = rbase + h * 64 + (ib * 4 + i) * 8;
;               const u32x4 a = *(const u32x4*)(wst + ((ib * 4 + i) * 8 + (lane >> 3)) * 128 + (((lane & 7) ^ rswz) << 4));
;               u32x4 o;
; #pragma unroll
;               for (int c = 0; c < 4; ++c) {
;                 const float lo = bflo(a[c]) * bflo(g1v[i][c]) + bflo(pv[i][c]) * (bflo(g0v[i][c]) - bflo(g1v[i][c]));
;                 const float hi = bfhi(a[c]) * bfhi(g1v[i][c]) + bfhi(pv[i][c]) * (bfhi(g0v[i][c]) - bfhi(g1v[i][c]));
;                 o[c] = pack2(lo, hi);
;               }
;               *(u32x4*)(p.hbuf() + gr * DM + cbase) = o;
	v_lshlrev_b32_e32 v132, 16, v96
	v_pk_fma_f32 v[126:127], v[128:129], v[130:131], v[126:127]
	s_waitcnt vmcnt(7)
	v_lshlrev_b32_e32 v128, 16, v100
	v_cvt_pk_bf16_f32 v123, v126, v127
	v_lshl_add_u64 v[126:127], s[12:13], 0, v[110:111]
	v_lshl_add_u64 v[126:127], v[126:127], 0, v[108:109]
	global_store_dwordx4 v[126:127], v[120:123], off
	ds_read_b128 v[120:123], v116 offset:5120
	v_and_b32_e32 v129, 0xffff0000, v100
	v_and_b32_e32 v133, 0xffff0000, v96
	s_waitcnt vmcnt(7)
	v_lshlrev_b32_e32 v130, 16, v104
	v_and_b32_e32 v131, 0xffff0000, v104
	s_waitcnt lgkmcnt(0)
	v_lshlrev_b32_e32 v126, 16, v120
	v_and_b32_e32 v127, 0xffff0000, v120
	v_pk_mul_f32 v[126:127], v[128:129], v[126:127]
	v_pk_add_f32 v[128:129], v[132:133], v[128:129] neg_lo:[0,1] neg_hi:[0,1]
	v_lshlrev_b32_e32 v120, 16, v121
	v_pk_fma_f32 v[126:127], v[128:129], v[130:131], v[126:127]
	v_and_b32_e32 v121, 0xffff0000, v121
	v_cvt_pk_bf16_f32 v96, v126, v127
	v_lshlrev_b32_e32 v100, 16, v101
	v_and_b32_e32 v101, 0xffff0000, v101
	v_lshlrev_b32_e32 v126, 16, v97
	v_and_b32_e32 v127, 0xffff0000, v97
	v_pk_mul_f32 v[120:121], v[100:101], v[120:121]
	v_lshlrev_b32_e32 v104, 16, v105
	v_and_b32_e32 v105, 0xffff0000, v105
	v_pk_add_f32 v[100:101], v[126:127], v[100:101] neg_lo:[0,1] neg_hi:[0,1]
	v_lshlrev_b32_e32 v126, 16, v98
	v_pk_fma_f32 v[100:101], v[100:101], v[104:105], v[120:121]
	v_lshlrev_b32_e32 v104, 16, v102
	v_cvt_pk_bf16_f32 v97, v100, v101
	v_lshlrev_b32_e32 v100, 16, v122
	v_and_b32_e32 v101, 0xffff0000, v122
	v_and_b32_e32 v105, 0xffff0000, v102
	v_and_b32_e32 v127, 0xffff0000, v98
	v_pk_mul_f32 v[100:101], v[104:105], v[100:101]
	v_lshlrev_b32_e32 v120, 16, v106
	v_and_b32_e32 v121, 0xffff0000, v106
	v_pk_add_f32 v[104:105], v[126:127], v[104:105] neg_lo:[0,1] neg_hi:[0,1]
	v_lshlrev_b32_e32 v102, 16, v103
	v_pk_fma_f32 v[100:101], v[104:105], v[120:121], v[100:101]
	v_and_b32_e32 v103, 0xffff0000, v103
	v_cvt_pk_bf16_f32 v98, v100, v101
	v_lshlrev_b32_e32 v100, 16, v123
	v_and_b32_e32 v101, 0xffff0000, v123
	v_lshlrev_b32_e32 v104, 16, v107
	v_and_b32_e32 v105, 0xffff0000, v107
	v_lshlrev_b32_e32 v106, 16, v99
	v_and_b32_e32 v107, 0xffff0000, v99
	v_pk_mul_f32 v[100:101], v[102:103], v[100:101]
	v_pk_add_f32 v[102:103], v[106:107], v[102:103] neg_lo:[0,1] neg_hi:[0,1]
	v_readlane_b32 s12, v254, 50
	v_pk_fma_f32 v[100:101], v[102:103], v[104:105], v[100:101]
	v_readlane_b32 s13, v254, 51
	v_cvt_pk_bf16_f32 v99, v100, v101
	s_waitcnt vmcnt(5)
	v_lshlrev_b32_e32 v102, 16, v88
	v_lshl_add_u64 v[100:101], s[12:13], 0, v[110:111]
	v_lshl_add_u64 v[100:101], v[100:101], 0, v[108:109]
	global_store_dwordx4 v[100:101], v[96:99], off
	ds_read_b128 v[96:99], v116 offset:6144
	v_and_b32_e32 v103, 0xffff0000, v88
	v_lshlrev_b32_e32 v106, 16, v84
	v_and_b32_e32 v107, 0xffff0000, v84
	s_waitcnt vmcnt(5)
	v_lshlrev_b32_e32 v104, 16, v92
	s_waitcnt lgkmcnt(0)
	v_lshlrev_b32_e32 v100, 16, v96
	v_and_b32_e32 v101, 0xffff0000, v96
	v_pk_mul_f32 v[100:101], v[102:103], v[100:101]
	v_and_b32_e32 v105, 0xffff0000, v92
	v_pk_add_f32 v[102:103], v[106:107], v[102:103] neg_lo:[0,1] neg_hi:[0,1]
	v_lshlrev_b32_e32 v96, 16, v97
	v_pk_fma_f32 v[100:101], v[102:103], v[104:105], v[100:101]
	v_and_b32_e32 v97, 0xffff0000, v97
	v_cvt_pk_bf16_f32 v84, v100, v101
	v_lshlrev_b32_e32 v88, 16, v89
	v_and_b32_e32 v89, 0xffff0000, v89
	v_lshlrev_b32_e32 v100, 16, v85
	v_and_b32_e32 v101, 0xffff0000, v85
	v_pk_mul_f32 v[96:97], v[88:89], v[96:97]
	v_lshlrev_b32_e32 v92, 16, v93
	v_and_b32_e32 v93, 0xffff0000, v93
	v_pk_add_f32 v[88:89], v[100:101], v[88:89] neg_lo:[0,1] neg_hi:[0,1]
	v_lshlrev_b32_e32 v100, 16, v86
	v_pk_fma_f32 v[88:89], v[88:89], v[92:93], v[96:97]
	v_lshlrev_b32_e32 v92, 16, v90
	v_cvt_pk_bf16_f32 v85, v88, v89
	v_lshlrev_b32_e32 v88, 16, v98
	v_and_b32_e32 v89, 0xffff0000, v98
	v_and_b32_e32 v93, 0xffff0000, v90
	v_and_b32_e32 v101, 0xffff0000, v86
	v_pk_mul_f32 v[88:89], v[92:93], v[88:89]
	v_lshlrev_b32_e32 v96, 16, v94
	v_and_b32_e32 v97, 0xffff0000, v94
	v_pk_add_f32 v[92:93], v[100:101], v[92:93] neg_lo:[0,1] neg_hi:[0,1]
	v_lshlrev_b32_e32 v90, 16, v91
	v_pk_fma_f32 v[88:89], v[92:93], v[96:97], v[88:89]
	v_and_b32_e32 v91, 0xffff0000, v91
	v_cvt_pk_bf16_f32 v86, v88, v89
	v_lshlrev_b32_e32 v88, 16, v99
	v_and_b32_e32 v89, 0xffff0000, v99
	v_lshlrev_b32_e32 v92, 16, v95
	v_and_b32_e32 v93, 0xffff0000, v95
	v_lshlrev_b32_e32 v94, 16, v87
	v_and_b32_e32 v95, 0xffff0000, v87
	v_pk_mul_f32 v[88:89], v[90:91], v[88:89]
	v_pk_add_f32 v[90:91], v[94:95], v[90:91] neg_lo:[0,1] neg_hi:[0,1]
	v_readlane_b32 s12, v254, 52
	v_pk_fma_f32 v[88:89], v[90:91], v[92:93], v[88:89]
	v_readlane_b32 s13, v254, 53
	v_cvt_pk_bf16_f32 v87, v88, v89
	s_waitcnt vmcnt(3)
	v_lshlrev_b32_e32 v90, 16, v76
	v_lshl_add_u64 v[88:89], s[12:13], 0, v[110:111]
	v_lshl_add_u64 v[88:89], v[88:89], 0, v[108:109]
	global_store_dwordx4 v[88:89], v[84:87], off
	ds_read_b128 v[84:87], v116 offset:7168
	v_and_b32_e32 v91, 0xffff0000, v76
	v_lshlrev_b32_e32 v94, 16, v72
	v_and_b32_e32 v95, 0xffff0000, v72
	s_waitcnt vmcnt(3)
	v_lshlrev_b32_e32 v92, 16, v80
	s_waitcnt lgkmcnt(0)
;   __device__ __forceinline__ u16* hbuf() const { return (u16*)(ws + 57 * MB); }
;   __device__ __forceinline__ u16* proj() const { return (u16*)(ws + 185 * MB); }
; __device__ __forceinline__ float bflo(unsigned u) { return __uint_as_float(u << 16); }
; __device__ __forceinline__ float bfhi(unsigned u) { return __uint_as_float(u & 0xffff0000u); }
; #define LDS_FENCE() asm volatile("s_waitcnt lgkmcnt(0)" ::: "memory")
; template <int EPI> ...
;     ...
; #pragma unroll
;         for (int h = 0; h < 2; ++h) {
; #pragma unroll
;           for (int mm = 0; mm < 4; ++mm)
; #pragma unroll
;             for (int n = 0; n < 4; ++n) {
;               const f32x4 v = acc[h * 4 + mm][n];
;               u32x2 o = {pack2(v[0], v[1]), pack2(v[2], v[3])};
;               *(u32x2*)(wst + (mm * 16 + fr) * 128 + (((n * 2 + (fq >> 1)) ^ wswz) << 4) + (fq & 1) * 8) = o;
;             }
;           LDS_FENCE();
; #pragma unroll
;           for (int ib = 0; ib < 2; ++ib) {
;             u32x4 g0v[4], g1v[4], pv[4];
; #pragma unroll
;             for (int i = 0; i < 4; ++i) {
;               const long gr = rbase + h * 64 + (ib * 4 + i) * 8;
;               g0v[i] = *(const u32x4*)(p.proj() + gr * INW + 2304 + cbase);
;               g1v[i] = *(const u32x4*)(p.proj() + gr * INW + 3328 + cbase);
;               pv[i] = *(const u32x4*)(p.hbuf() + gr * DM + cbase);
;             }
; #pragma unroll
;             for (int i = 0; i < 4; ++i) {
;               const long gr = rbase + h * 64 + (ib * 4 + i) * 8;
;               const u32x4 a = *(const u32x4*)(wst + ((ib * 4 + i) * 8 + (lane >> 3)) * 128 + (((lane & 7) ^ rswz) << 4));
;               u32x4 o;
; #pragma unroll
;               for (int c = 0; c < 4; ++c) {
;                 const float lo = bflo(a[c]) * bflo(g1v[i][c]) + bflo(pv[i][c]) * (bflo(g0v[i][c]) - bflo(g1v[i][c]));
;                 const float hi = bfhi(a[c]) * bfhi(g1v[i][c]) + bfhi(pv[i][c]) * (bfhi(g0v[i][c]) - bfhi(g1v[i][c]));
;                 o[c] = pack2(lo, hi);
;               }
;               *(u32x4*)(p.hbuf() + gr * DM + cbase) = o;
;             }
	v_lshlrev_b32_e32 v88, 16, v84
	v_and_b32_e32 v89, 0xffff0000, v84
	v_pk_mul_f32 v[88:89], v[90:91], v[88:89]
	v_and_b32_e32 v93, 0xffff0000, v80
	v_pk_add_f32 v[90:91], v[94:95], v[90:91] neg_lo:[0,1] neg_hi:[0,1]
	v_lshlrev_b32_e32 v84, 16, v85
	v_pk_fma_f32 v[88:89], v[90:91], v[92:93], v[88:89]
	v_and_b32_e32 v85, 0xffff0000, v85
	v_cvt_pk_bf16_f32 v72, v88, v89
	v_lshlrev_b32_e32 v76, 16, v77
	v_and_b32_e32 v77, 0xffff0000, v77
	v_lshlrev_b32_e32 v88, 16, v73
	v_and_b32_e32 v89, 0xffff0000, v73
	v_pk_mul_f32 v[84:85], v[76:77], v[84:85]
	v_lshlrev_b32_e32 v80, 16, v81
	v_and_b32_e32 v81, 0xffff0000, v81
	v_pk_add_f32 v[76:77], v[88:89], v[76:77] neg_lo:[0,1] neg_hi:[0,1]
	v_lshlrev_b32_e32 v88, 16, v74
	v_pk_fma_f32 v[76:77], v[76:77], v[80:81], v[84:85]
	v_lshlrev_b32_e32 v80, 16, v78
	v_cvt_pk_bf16_f32 v73, v76, v77
	v_lshlrev_b32_e32 v76, 16, v86
	v_and_b32_e32 v77, 0xffff0000, v86
	v_and_b32_e32 v81, 0xffff0000, v78
	v_and_b32_e32 v89, 0xffff0000, v74
	v_pk_mul_f32 v[76:77], v[80:81], v[76:77]
	v_lshlrev_b32_e32 v84, 16, v82
	v_and_b32_e32 v85, 0xffff0000, v82
	v_pk_add_f32 v[80:81], v[88:89], v[80:81] neg_lo:[0,1] neg_hi:[0,1]
	v_lshlrev_b32_e32 v78, 16, v79
	v_pk_fma_f32 v[76:77], v[80:81], v[84:85], v[76:77]
	v_and_b32_e32 v79, 0xffff0000, v79
	v_cvt_pk_bf16_f32 v74, v76, v77
	v_lshlrev_b32_e32 v76, 16, v87
	v_and_b32_e32 v77, 0xffff0000, v87
	v_lshlrev_b32_e32 v80, 16, v83
	v_and_b32_e32 v81, 0xffff0000, v83
	v_lshlrev_b32_e32 v82, 16, v75
	v_and_b32_e32 v83, 0xffff0000, v75
	v_pk_mul_f32 v[76:77], v[78:79], v[76:77]
	v_pk_add_f32 v[78:79], v[82:83], v[78:79] neg_lo:[0,1] neg_hi:[0,1]
	v_readlane_b32 s12, v254, 54
	v_pk_fma_f32 v[76:77], v[78:79], v[80:81], v[76:77]
	v_readlane_b32 s13, v254, 55
	v_cvt_pk_bf16_f32 v75, v76, v77
	s_nop 0
	v_lshl_add_u64 v[76:77], s[12:13], 0, v[110:111]
	v_lshl_add_u64 v[76:77], v[76:77], 0, v[108:109]
	global_store_dwordx4 v[76:77], v[72:75], off
	v_cvt_pk_bf16_f32 v56, v56, v57
	v_cvt_pk_bf16_f32 v57, v58, v59
	v_cvt_pk_bf16_f32 v40, v40, v41
	v_cvt_pk_bf16_f32 v41, v42, v43
	v_cvt_pk_bf16_f32 v24, v24, v25
	v_cvt_pk_bf16_f32 v25, v26, v27
	v_cvt_pk_bf16_f32 v8, v8, v9
	v_cvt_pk_bf16_f32 v9, v10, v11
	s_waitcnt lgkmcnt(0)
	v_cvt_pk_bf16_f32 v58, v68, v69
	v_cvt_pk_bf16_f32 v59, v70, v71
	ds_write2st64_b64 v117, v[56:57], v[40:41] offset1:4
	v_cvt_pk_bf16_f32 v40, v52, v53
	v_cvt_pk_bf16_f32 v41, v54, v55
	v_cvt_pk_bf16_f32 v26, v36, v37
	v_cvt_pk_bf16_f32 v27, v38, v39
	ds_write2st64_b64 v117, v[24:25], v[8:9] offset0:8 offset1:12
	v_cvt_pk_bf16_f32 v8, v20, v21
	v_cvt_pk_bf16_f32 v9, v22, v23
	v_cvt_pk_bf16_f32 v60, v60, v61
	v_cvt_pk_bf16_f32 v61, v62, v63
	v_cvt_pk_bf16_f32 v62, v64, v65
	v_cvt_pk_bf16_f32 v63, v66, v67
	v_cvt_pk_bf16_f32 v44, v44, v45
	v_cvt_pk_bf16_f32 v45, v46, v47
	ds_write2st64_b64 v118, v[58:59], v[40:41] offset1:4
	v_cvt_pk_bf16_f32 v40, v48, v49
	v_cvt_pk_bf16_f32 v41, v50, v51
	v_cvt_pk_bf16_f32 v28, v28, v29
	v_cvt_pk_bf16_f32 v29, v30, v31
	v_cvt_pk_bf16_f32 v30, v32, v33
	v_cvt_pk_bf16_f32 v31, v34, v35
	v_cvt_pk_bf16_f32 v12, v12, v13
	v_cvt_pk_bf16_f32 v13, v14, v15
	ds_write2st64_b64 v118, v[26:27], v[8:9] offset0:8 offset1:12
	v_cvt_pk_bf16_f32 v8, v16, v17
	v_cvt_pk_bf16_f32 v9, v18, v19
	s_mov_b32 s12, 0x89000
	ds_write2st64_b64 v124, v[60:61], v[44:45] offset1:4
	ds_write2st64_b64 v119, v[62:63], v[40:41] offset1:4
	ds_write2st64_b64 v124, v[28:29], v[12:13] offset0:8 offset1:12
	ds_write2st64_b64 v119, v[30:31], v[8:9] offset0:8 offset1:12
	v_add_co_u32_e32 v8, vcc, s12, v114
	s_waitcnt lgkmcnt(0)
	s_mov_b32 s12, 0x9a000
	s_nop 0
	v_addc_co_u32_e32 v9, vcc, 0, v115, vcc
	global_load_dwordx4 v[44:47], v[8:9], off offset:512 nt
	global_load_dwordx4 v[48:51], v[8:9], off offset:2560 nt
	v_or_b32_e32 v8, 0x20000, v110
	v_mov_b32_e32 v9, v111
	v_lshl_add_u64 v[8:9], v[112:113], 0, v[8:9]
	global_load_dwordx4 v[52:55], v[8:9], off nt
	v_add_co_u32_e32 v8, vcc, s12, v114
	s_mov_b32 s12, 0xab000
	s_nop 0
	v_addc_co_u32_e32 v9, vcc, 0, v115, vcc
	global_load_dwordx4 v[32:35], v[8:9], off offset:512 nt
	global_load_dwordx4 v[36:39], v[8:9], off offset:2560 nt
	v_or_b32_e32 v8, 0x24000, v110
	v_mov_b32_e32 v9, v111
	v_lshl_add_u64 v[8:9], v[112:113], 0, v[8:9]
	global_load_dwordx4 v[40:43], v[8:9], off nt
	v_add_co_u32_e32 v8, vcc, s12, v114
	s_mov_b32 s12, 0xbc000
	s_nop 0
	v_addc_co_u32_e32 v9, vcc, 0, v115, vcc
	global_load_dwordx4 v[20:23], v[8:9], off offset:512 nt
	global_load_dwordx4 v[24:27], v[8:9], off offset:2560 nt
	v_or_b32_e32 v8, 0x28000, v110
	v_mov_b32_e32 v9, v111
	v_lshl_add_u64 v[8:9], v[112:113], 0, v[8:9]
	global_load_dwordx4 v[28:31], v[8:9], off nt
	v_add_co_u32_e32 v12, vcc, s12, v114
	v_readlane_b32 s12, v254, 56
	s_nop 0
	v_addc_co_u32_e32 v13, vcc, 0, v115, vcc
	global_load_dwordx4 v[8:11], v[12:13], off offset:512 nt
	global_load_dwordx4 v[16:19], v[12:13], off offset:2560 nt
	v_or_b32_e32 v12, 0x2c000, v110
	v_mov_b32_e32 v13, v111
	v_lshl_add_u64 v[12:13], v[112:113], 0, v[12:13]
	global_load_dwordx4 v[12:15], v[12:13], off nt
	ds_read_b128 v[56:59], v116
	v_readlane_b32 s13, v254, 57
	s_waitcnt lgkmcnt(0)
	v_lshlrev_b32_e32 v60, 16, v56
	v_and_b32_e32 v61, 0xffff0000, v56
	v_lshlrev_b32_e32 v56, 16, v57
	v_and_b32_e32 v57, 0xffff0000, v57
	s_waitcnt vmcnt(11)
	v_lshlrev_b32_e32 v66, 16, v44
	s_waitcnt vmcnt(10)
	v_lshlrev_b32_e32 v62, 16, v48
	v_and_b32_e32 v63, 0xffff0000, v48
	v_and_b32_e32 v67, 0xffff0000, v44
	v_pk_mul_f32 v[60:61], v[62:63], v[60:61]
	s_waitcnt vmcnt(9)
;   __device__ __forceinline__ u16* hbuf() const { return (u16*)(ws + 57 * MB); }
; __device__ __forceinline__ float bflo(unsigned u) { return __uint_as_float(u << 16); }
; __device__ __forceinline__ float bfhi(unsigned u) { return __uint_as_float(u & 0xffff0000u); }
; template <int EPI> ...
;     ...
; #pragma unroll
;             for (int i = 0; i < 4; ++i) {
;               const long gr = rbase + h * 64 + (ib * 4 + i) * 8;
;               const u32x4 a = *(const u32x4*)(wst + ((ib * 4 + i) * 8 + (lane >> 3)) * 128 + (((lane & 7) ^ rswz) << 4));
;               u32x4 o;
; #pragma unroll
;               for (int c = 0; c < 4; ++c) {
;                 const float lo = bflo(a[c]) * bflo(g1v[i][c]) + bflo(pv[i][c]) * (bflo(g0v[i][c]) - bflo(g1v[i][c]));
;                 const float hi = bfhi(a[c]) * bfhi(g1v[i][c]) + bfhi(pv[i][c]) * (bfhi(g0v[i][c]) - bfhi(g1v[i][c]));
;                 o[c] = pack2(lo, hi);
;               }
;               *(u32x4*)(p.hbuf() + gr * DM + cbase) = o;
;             }
	v_lshlrev_b32_e32 v64, 16, v52
	v_and_b32_e32 v65, 0xffff0000, v52
	v_pk_add_f32 v[62:63], v[66:67], v[62:63] neg_lo:[0,1] neg_hi:[0,1]
	v_lshlrev_b32_e32 v48, 16, v49
	v_pk_fma_f32 v[60:61], v[62:63], v[64:65], v[60:61]
	v_and_b32_e32 v49, 0xffff0000, v49
	v_cvt_pk_bf16_f32 v44, v60, v61
	v_lshlrev_b32_e32 v60, 16, v45
	v_and_b32_e32 v61, 0xffff0000, v45
	v_pk_mul_f32 v[56:57], v[48:49], v[56:57]
	v_lshlrev_b32_e32 v52, 16, v53
	v_and_b32_e32 v53, 0xffff0000, v53
	v_pk_add_f32 v[48:49], v[60:61], v[48:49] neg_lo:[0,1] neg_hi:[0,1]
	v_lshlrev_b32_e32 v60, 16, v46
	v_pk_fma_f32 v[48:49], v[48:49], v[52:53], v[56:57]
	v_lshlrev_b32_e32 v52, 16, v50
	v_cvt_pk_bf16_f32 v45, v48, v49
	v_lshlrev_b32_e32 v48, 16, v58
	v_and_b32_e32 v49, 0xffff0000, v58
	v_and_b32_e32 v53, 0xffff0000, v50
	v_and_b32_e32 v61, 0xffff0000, v46
	v_pk_mul_f32 v[48:49], v[52:53], v[48:49]
	v_lshlrev_b32_e32 v56, 16, v54
	v_and_b32_e32 v57, 0xffff0000, v54
	v_pk_add_f32 v[52:53], v[60:61], v[52:53] neg_lo:[0,1] neg_hi:[0,1]
	v_lshlrev_b32_e32 v50, 16, v51
	v_pk_fma_f32 v[48:49], v[52:53], v[56:57], v[48:49]
	v_and_b32_e32 v51, 0xffff0000, v51
	v_cvt_pk_bf16_f32 v46, v48, v49
	v_lshlrev_b32_e32 v48, 16, v59
	v_and_b32_e32 v49, 0xffff0000, v59
	v_lshlrev_b32_e32 v52, 16, v55
	v_and_b32_e32 v53, 0xffff0000, v55
	v_lshlrev_b32_e32 v54, 16, v47
	v_and_b32_e32 v55, 0xffff0000, v47
	v_pk_mul_f32 v[48:49], v[50:51], v[48:49]
	v_pk_add_f32 v[50:51], v[54:55], v[50:51] neg_lo:[0,1] neg_hi:[0,1]
	s_waitcnt vmcnt(8)
	v_lshlrev_b32_e32 v54, 16, v32
	v_pk_fma_f32 v[48:49], v[50:51], v[52:53], v[48:49]
	s_waitcnt vmcnt(7)
	v_lshlrev_b32_e32 v50, 16, v36
	v_cvt_pk_bf16_f32 v47, v48, v49
	v_lshl_add_u64 v[48:49], s[12:13], 0, v[110:111]
	v_lshl_add_u64 v[48:49], v[48:49], 0, v[108:109]
	global_store_dwordx4 v[48:49], v[44:47], off
	ds_read_b128 v[44:47], v116 offset:1024
	v_and_b32_e32 v51, 0xffff0000, v36
	v_and_b32_e32 v55, 0xffff0000, v32
	s_waitcnt vmcnt(7)
	v_lshlrev_b32_e32 v52, 16, v40
	v_and_b32_e32 v53, 0xffff0000, v40
	s_waitcnt lgkmcnt(0)
	v_lshlrev_b32_e32 v48, 16, v44
	v_and_b32_e32 v49, 0xffff0000, v44
	v_pk_mul_f32 v[48:49], v[50:51], v[48:49]
	v_pk_add_f32 v[50:51], v[54:55], v[50:51] neg_lo:[0,1] neg_hi:[0,1]
	v_lshlrev_b32_e32 v44, 16, v45
	v_pk_fma_f32 v[48:49], v[50:51], v[52:53], v[48:49]
	v_and_b32_e32 v45, 0xffff0000, v45
	v_cvt_pk_bf16_f32 v32, v48, v49
	v_lshlrev_b32_e32 v36, 16, v37
	v_and_b32_e32 v37, 0xffff0000, v37
	v_lshlrev_b32_e32 v48, 16, v33
	v_and_b32_e32 v49, 0xffff0000, v33
	v_pk_mul_f32 v[44:45], v[36:37], v[44:45]
	v_lshlrev_b32_e32 v40, 16, v41
	v_and_b32_e32 v41, 0xffff0000, v41
	v_pk_add_f32 v[36:37], v[48:49], v[36:37] neg_lo:[0,1] neg_hi:[0,1]
	v_lshlrev_b32_e32 v48, 16, v34
	v_pk_fma_f32 v[36:37], v[36:37], v[40:41], v[44:45]
	v_lshlrev_b32_e32 v40, 16, v38
	v_cvt_pk_bf16_f32 v33, v36, v37
	v_lshlrev_b32_e32 v36, 16, v46
	v_and_b32_e32 v37, 0xffff0000, v46
	v_and_b32_e32 v41, 0xffff0000, v38
	v_and_b32_e32 v49, 0xffff0000, v34
	v_pk_mul_f32 v[36:37], v[40:41], v[36:37]
	v_lshlrev_b32_e32 v44, 16, v42
	v_and_b32_e32 v45, 0xffff0000, v42
	v_pk_add_f32 v[40:41], v[48:49], v[40:41] neg_lo:[0,1] neg_hi:[0,1]
	v_lshlrev_b32_e32 v38, 16, v39
	v_pk_fma_f32 v[36:37], v[40:41], v[44:45], v[36:37]
	v_and_b32_e32 v39, 0xffff0000, v39
	v_cvt_pk_bf16_f32 v34, v36, v37
	v_lshlrev_b32_e32 v36, 16, v47
	v_and_b32_e32 v37, 0xffff0000, v47
	v_lshlrev_b32_e32 v40, 16, v43
	v_and_b32_e32 v41, 0xffff0000, v43
	v_lshlrev_b32_e32 v42, 16, v35
	v_and_b32_e32 v43, 0xffff0000, v35
	v_pk_mul_f32 v[36:37], v[38:39], v[36:37]
	v_pk_add_f32 v[38:39], v[42:43], v[38:39] neg_lo:[0,1] neg_hi:[0,1]
	v_readlane_b32 s12, v254, 58
	v_pk_fma_f32 v[36:37], v[38:39], v[40:41], v[36:37]
	v_readlane_b32 s13, v254, 59
	v_cvt_pk_bf16_f32 v35, v36, v37
	s_waitcnt vmcnt(5)
	v_lshlrev_b32_e32 v38, 16, v24
	v_lshl_add_u64 v[36:37], s[12:13], 0, v[110:111]
	v_lshl_add_u64 v[36:37], v[36:37], 0, v[108:109]
	global_store_dwordx4 v[36:37], v[32:35], off
	ds_read_b128 v[32:35], v116 offset:2048
	v_and_b32_e32 v39, 0xffff0000, v24
	v_lshlrev_b32_e32 v42, 16, v20
	v_and_b32_e32 v43, 0xffff0000, v20
	s_waitcnt vmcnt(5)
	v_lshlrev_b32_e32 v40, 16, v28
	s_waitcnt lgkmcnt(0)
	v_lshlrev_b32_e32 v36, 16, v32
	v_and_b32_e32 v37, 0xffff0000, v32
	v_pk_mul_f32 v[36:37], v[38:39], v[36:37]
	v_and_b32_e32 v41, 0xffff0000, v28
	v_pk_add_f32 v[38:39], v[42:43], v[38:39] neg_lo:[0,1] neg_hi:[0,1]
	v_lshlrev_b32_e32 v32, 16, v33
	v_pk_fma_f32 v[36:37], v[38:39], v[40:41], v[36:37]
	v_and_b32_e32 v33, 0xffff0000, v33
	v_cvt_pk_bf16_f32 v20, v36, v37
	v_lshlrev_b32_e32 v24, 16, v25
	v_and_b32_e32 v25, 0xffff0000, v25
	v_lshlrev_b32_e32 v36, 16, v21
	v_and_b32_e32 v37, 0xffff0000, v21
	v_pk_mul_f32 v[32:33], v[24:25], v[32:33]
	v_lshlrev_b32_e32 v28, 16, v29
	v_and_b32_e32 v29, 0xffff0000, v29
	v_pk_add_f32 v[24:25], v[36:37], v[24:25] neg_lo:[0,1] neg_hi:[0,1]
	v_lshlrev_b32_e32 v36, 16, v22
	v_pk_fma_f32 v[24:25], v[24:25], v[28:29], v[32:33]
	v_lshlrev_b32_e32 v28, 16, v26
	v_cvt_pk_bf16_f32 v21, v24, v25
	v_lshlrev_b32_e32 v24, 16, v34
	v_and_b32_e32 v25, 0xffff0000, v34
	v_and_b32_e32 v29, 0xffff0000, v26
	v_and_b32_e32 v37, 0xffff0000, v22
	v_pk_mul_f32 v[24:25], v[28:29], v[24:25]
	v_lshlrev_b32_e32 v32, 16, v30
	v_and_b32_e32 v33, 0xffff0000, v30
	v_pk_add_f32 v[28:29], v[36:37], v[28:29] neg_lo:[0,1] neg_hi:[0,1]
	v_lshlrev_b32_e32 v26, 16, v27
	v_pk_fma_f32 v[24:25], v[28:29], v[32:33], v[24:25]
	v_and_b32_e32 v27, 0xffff0000, v27
	v_cvt_pk_bf16_f32 v22, v24, v25
	v_lshlrev_b32_e32 v24, 16, v35
	v_and_b32_e32 v25, 0xffff0000, v35
	v_lshlrev_b32_e32 v28, 16, v31
	v_and_b32_e32 v29, 0xffff0000, v31
	v_lshlrev_b32_e32 v30, 16, v23
	v_and_b32_e32 v31, 0xffff0000, v23
	v_pk_mul_f32 v[24:25], v[26:27], v[24:25]
	v_pk_add_f32 v[26:27], v[30:31], v[26:27] neg_lo:[0,1] neg_hi:[0,1]
	v_readlane_b32 s12, v254, 60
	v_pk_fma_f32 v[24:25], v[26:27], v[28:29], v[24:25]
	v_readlane_b32 s13, v254, 61
	v_cvt_pk_bf16_f32 v23, v24, v25
	s_waitcnt vmcnt(3)
;   __device__ __forceinline__ u16* hbuf() const { return (u16*)(ws + 57 * MB); }
;   __device__ __forceinline__ u16* proj() const { return (u16*)(ws + 185 * MB); }
; __device__ __forceinline__ float bflo(unsigned u) { return __uint_as_float(u << 16); }
; __device__ __forceinline__ float bfhi(unsigned u) { return __uint_as_float(u & 0xffff0000u); }
; template <int EPI> ...
;     ...
;           for (int ib = 0; ib < 2; ++ib) {
;             u32x4 g0v[4], g1v[4], pv[4];
; #pragma unroll
;             for (int i = 0; i < 4; ++i) {
;               const long gr = rbase + h * 64 + (ib * 4 + i) * 8;
;               g0v[i] = *(const u32x4*)(p.proj() + gr * INW + 2304 + cbase);
;               g1v[i] = *(const u32x4*)(p.proj() + gr * INW + 3328 + cbase);
;               pv[i] = *(const u32x4*)(p.hbuf() + gr * DM + cbase);
;             }
; #pragma unroll
;             for (int i = 0; i < 4; ++i) {
;               const long gr = rbase + h * 64 + (ib * 4 + i) * 8;
;               const u32x4 a = *(const u32x4*)(wst + ((ib * 4 + i) * 8 + (lane >> 3)) * 128 + (((lane & 7) ^ rswz) << 4));
;               u32x4 o;
; #pragma unroll
;               for (int c = 0; c < 4; ++c) {
;                 const float lo = bflo(a[c]) * bflo(g1v[i][c]) + bflo(pv[i][c]) * (bflo(g0v[i][c]) - bflo(g1v[i][c]));
;                 const float hi = bfhi(a[c]) * bfhi(g1v[i][c]) + bfhi(pv[i][c]) * (bfhi(g0v[i][c]) - bfhi(g1v[i][c]));
;                 o[c] = pack2(lo, hi);
;               }
;               *(u32x4*)(p.hbuf() + gr * DM + cbase) = o;
;             }
	v_lshlrev_b32_e32 v26, 16, v16
	v_lshl_add_u64 v[24:25], s[12:13], 0, v[110:111]
	v_lshl_add_u64 v[24:25], v[24:25], 0, v[108:109]
	global_store_dwordx4 v[24:25], v[20:23], off
	ds_read_b128 v[20:23], v116 offset:3072
	v_and_b32_e32 v27, 0xffff0000, v16
	v_lshlrev_b32_e32 v30, 16, v8
	v_and_b32_e32 v31, 0xffff0000, v8
	s_waitcnt vmcnt(3)
	v_lshlrev_b32_e32 v28, 16, v12
	s_waitcnt lgkmcnt(0)
	v_lshlrev_b32_e32 v24, 16, v20
	v_and_b32_e32 v25, 0xffff0000, v20
	v_pk_mul_f32 v[24:25], v[26:27], v[24:25]
	v_and_b32_e32 v29, 0xffff0000, v12
	v_pk_add_f32 v[26:27], v[30:31], v[26:27] neg_lo:[0,1] neg_hi:[0,1]
	v_lshlrev_b32_e32 v20, 16, v21
	v_pk_fma_f32 v[24:25], v[26:27], v[28:29], v[24:25]
	v_and_b32_e32 v21, 0xffff0000, v21
	v_cvt_pk_bf16_f32 v8, v24, v25
	v_lshlrev_b32_e32 v16, 16, v17
	v_and_b32_e32 v17, 0xffff0000, v17
	v_lshlrev_b32_e32 v24, 16, v9
	v_and_b32_e32 v25, 0xffff0000, v9
	v_pk_mul_f32 v[20:21], v[16:17], v[20:21]
	v_lshlrev_b32_e32 v12, 16, v13
	v_and_b32_e32 v13, 0xffff0000, v13
	v_pk_add_f32 v[16:17], v[24:25], v[16:17] neg_lo:[0,1] neg_hi:[0,1]
	v_lshlrev_b32_e32 v24, 16, v10
	v_pk_fma_f32 v[12:13], v[16:17], v[12:13], v[20:21]
	v_lshlrev_b32_e32 v16, 16, v18
	v_cvt_pk_bf16_f32 v9, v12, v13
	v_lshlrev_b32_e32 v12, 16, v22
	v_and_b32_e32 v13, 0xffff0000, v22
	v_and_b32_e32 v17, 0xffff0000, v18
	v_and_b32_e32 v25, 0xffff0000, v10
	v_pk_mul_f32 v[12:13], v[16:17], v[12:13]
	v_lshlrev_b32_e32 v20, 16, v14
	v_and_b32_e32 v21, 0xffff0000, v14
	v_pk_add_f32 v[16:17], v[24:25], v[16:17] neg_lo:[0,1] neg_hi:[0,1]
	v_lshlrev_b32_e32 v18, 16, v11
	v_pk_fma_f32 v[12:13], v[16:17], v[20:21], v[12:13]
	v_lshlrev_b32_e32 v16, 16, v19
	v_cvt_pk_bf16_f32 v10, v12, v13
	v_lshlrev_b32_e32 v12, 16, v23
	v_and_b32_e32 v13, 0xffff0000, v23
	v_and_b32_e32 v17, 0xffff0000, v19
	v_and_b32_e32 v19, 0xffff0000, v11
	v_pk_mul_f32 v[12:13], v[16:17], v[12:13]
	v_lshlrev_b32_e32 v14, 16, v15
	v_and_b32_e32 v15, 0xffff0000, v15
	v_pk_add_f32 v[16:17], v[18:19], v[16:17] neg_lo:[0,1] neg_hi:[0,1]
	v_readlane_b32 s12, v254, 62
	v_pk_fma_f32 v[12:13], v[16:17], v[14:15], v[12:13]
	v_readlane_b32 s13, v254, 63
	v_cvt_pk_bf16_f32 v11, v12, v13
	s_nop 0
	v_lshl_add_u64 v[12:13], s[12:13], 0, v[110:111]
	v_lshl_add_u64 v[12:13], v[12:13], 0, v[108:109]
	global_store_dwordx4 v[12:13], v[8:11], off
	s_mov_b32 s12, 0xcd000
	s_nop 0
	v_add_co_u32_e32 v8, vcc, s12, v114
	s_mov_b32 s12, 0xde000
	s_nop 0
	v_addc_co_u32_e32 v9, vcc, 0, v115, vcc
	global_load_dwordx4 v[44:47], v[8:9], off offset:512 nt
	global_load_dwordx4 v[48:51], v[8:9], off offset:2560 nt
	v_or_b32_e32 v8, 0x30000, v110
	v_mov_b32_e32 v9, v111
	v_lshl_add_u64 v[8:9], v[112:113], 0, v[8:9]
	global_load_dwordx4 v[52:55], v[8:9], off nt
	v_add_co_u32_e32 v8, vcc, s12, v114
	s_mov_b32 s12, 0xef000
	s_nop 0
	v_addc_co_u32_e32 v9, vcc, 0, v115, vcc
	global_load_dwordx4 v[32:35], v[8:9], off offset:512 nt
	global_load_dwordx4 v[36:39], v[8:9], off offset:2560 nt
	v_or_b32_e32 v8, 0x34000, v110
	v_mov_b32_e32 v9, v111
	v_lshl_add_u64 v[8:9], v[112:113], 0, v[8:9]
	global_load_dwordx4 v[40:43], v[8:9], off nt
	v_add_co_u32_e32 v8, vcc, s12, v114
	s_mov_b32 s12, 0x100000
	s_nop 0
	v_addc_co_u32_e32 v9, vcc, 0, v115, vcc
	global_load_dwordx4 v[20:23], v[8:9], off offset:512 nt
	global_load_dwordx4 v[24:27], v[8:9], off offset:2560 nt
	v_or_b32_e32 v8, 0x38000, v110
	v_mov_b32_e32 v9, v111
	v_lshl_add_u64 v[8:9], v[112:113], 0, v[8:9]
	global_load_dwordx4 v[28:31], v[8:9], off nt
	v_add_co_u32_e32 v12, vcc, s12, v114
	v_or_b32_e32 v16, 0x3c000, v110
	s_nop 0
	v_addc_co_u32_e32 v13, vcc, 0, v115, vcc
	v_mov_b32_e32 v17, v111
	global_load_dwordx4 v[8:11], v[12:13], off offset:512 nt
	s_nop 0
	global_load_dwordx4 v[12:15], v[12:13], off offset:2560 nt
	v_lshl_add_u64 v[16:17], v[112:113], 0, v[16:17]
	global_load_dwordx4 v[16:19], v[16:17], off nt
	ds_read_b128 v[56:59], v116 offset:4096
	v_readlane_b32 s12, v255, 0
	v_readlane_b32 s13, v255, 1
	s_waitcnt lgkmcnt(0)
	v_lshlrev_b32_e32 v60, 16, v56
	v_and_b32_e32 v61, 0xffff0000, v56
	v_lshlrev_b32_e32 v56, 16, v57
	v_and_b32_e32 v57, 0xffff0000, v57
	s_waitcnt vmcnt(11)
	v_lshlrev_b32_e32 v66, 16, v44
	s_waitcnt vmcnt(10)
	v_lshlrev_b32_e32 v62, 16, v48
	v_and_b32_e32 v63, 0xffff0000, v48
	v_and_b32_e32 v67, 0xffff0000, v44
	v_pk_mul_f32 v[60:61], v[62:63], v[60:61]
	s_waitcnt vmcnt(9)
	v_lshlrev_b32_e32 v64, 16, v52
	v_and_b32_e32 v65, 0xffff0000, v52
	v_pk_add_f32 v[62:63], v[66:67], v[62:63] neg_lo:[0,1] neg_hi:[0,1]
	v_lshlrev_b32_e32 v48, 16, v49
	v_pk_fma_f32 v[60:61], v[62:63], v[64:65], v[60:61]
	v_and_b32_e32 v49, 0xffff0000, v49
	v_cvt_pk_bf16_f32 v44, v60, v61
	v_lshlrev_b32_e32 v60, 16, v45
	v_and_b32_e32 v61, 0xffff0000, v45
	v_pk_mul_f32 v[56:57], v[48:49], v[56:57]
	v_lshlrev_b32_e32 v52, 16, v53
	v_and_b32_e32 v53, 0xffff0000, v53
	v_pk_add_f32 v[48:49], v[60:61], v[48:49] neg_lo:[0,1] neg_hi:[0,1]
	v_lshlrev_b32_e32 v60, 16, v46
	v_pk_fma_f32 v[48:49], v[48:49], v[52:53], v[56:57]
	v_lshlrev_b32_e32 v52, 16, v50
	v_cvt_pk_bf16_f32 v45, v48, v49
	v_lshlrev_b32_e32 v48, 16, v58
	v_and_b32_e32 v49, 0xffff0000, v58
	v_and_b32_e32 v53, 0xffff0000, v50
	v_and_b32_e32 v61, 0xffff0000, v46
	v_pk_mul_f32 v[48:49], v[52:53], v[48:49]
	v_lshlrev_b32_e32 v56, 16, v54
	v_and_b32_e32 v57, 0xffff0000, v54
	v_pk_add_f32 v[52:53], v[60:61], v[52:53] neg_lo:[0,1] neg_hi:[0,1]
	v_lshlrev_b32_e32 v50, 16, v51
	v_pk_fma_f32 v[48:49], v[52:53], v[56:57], v[48:49]
	v_and_b32_e32 v51, 0xffff0000, v51
	v_cvt_pk_bf16_f32 v46, v48, v49
	v_lshlrev_b32_e32 v48, 16, v59
	v_and_b32_e32 v49, 0xffff0000, v59
	v_lshlrev_b32_e32 v52, 16, v55
	v_and_b32_e32 v53, 0xffff0000, v55
	v_lshlrev_b32_e32 v54, 16, v47
	v_and_b32_e32 v55, 0xffff0000, v47
	v_pk_mul_f32 v[48:49], v[50:51], v[48:49]
	v_pk_add_f32 v[50:51], v[54:55], v[50:51] neg_lo:[0,1] neg_hi:[0,1]
	s_waitcnt vmcnt(8)
;   __device__ __forceinline__ u16* hbuf() const { return (u16*)(ws + 57 * MB); }
; __device__ __forceinline__ float bflo(unsigned u) { return __uint_as_float(u << 16); }
; __device__ __forceinline__ float bfhi(unsigned u) { return __uint_as_float(u & 0xffff0000u); }
; #define GLDS_STAGE(Ap, Bp, buf, kt)                                                                                  \
;   do {                                                                                                               \
;     STAGE_Bm(0, 0, Bp, 0); STAGE_A(0, 0, Ap, 0); STAGE_Bm(0, 1, Bp, 0); STAGE_A(0, 1, Ap, 0);                        \
;   } while (0)
; #define LDS_FENCE() asm volatile("s_waitcnt lgkmcnt(0)" ::: "memory")
; template <int EPI> ...
;     ...
; #pragma unroll
;             for (int i = 0; i < 4; ++i) {
;               const long gr = rbase + h * 64 + (ib * 4 + i) * 8;
;               const u32x4 a = *(const u32x4*)(wst + ((ib * 4 + i) * 8 + (lane >> 3)) * 128 + (((lane & 7) ^ rswz) << 4));
;               u32x4 o;
; #pragma unroll
;               for (int c = 0; c < 4; ++c) {
;                 const float lo = bflo(a[c]) * bflo(g1v[i][c]) + bflo(pv[i][c]) * (bflo(g0v[i][c]) - bflo(g1v[i][c]));
;                 const float hi = bfhi(a[c]) * bfhi(g1v[i][c]) + bfhi(pv[i][c]) * (bfhi(g0v[i][c]) - bfhi(g1v[i][c]));
;                 o[c] = pack2(lo, hi);
;               }
;               *(u32x4*)(p.hbuf() + gr * DM + cbase) = o;
;             }
;             __builtin_amdgcn_sched_barrier(0);
;           }
;           LDS_FENCE();
;     ...
;       LDS_FENCE();
;       if constexpr (EPI == EPI_M0) {
;         if (have2) GLDS_STAGE(Ab2, Bb2, 0, 0);
	v_lshlrev_b32_e32 v54, 16, v32
	v_pk_fma_f32 v[48:49], v[50:51], v[52:53], v[48:49]
	s_waitcnt vmcnt(7)
	v_lshlrev_b32_e32 v50, 16, v36
	v_cvt_pk_bf16_f32 v47, v48, v49
	v_lshl_add_u64 v[48:49], s[12:13], 0, v[110:111]
	v_lshl_add_u64 v[48:49], v[48:49], 0, v[108:109]
	global_store_dwordx4 v[48:49], v[44:47], off
	ds_read_b128 v[44:47], v116 offset:5120
	v_and_b32_e32 v51, 0xffff0000, v36
	v_and_b32_e32 v55, 0xffff0000, v32
	s_waitcnt vmcnt(7)
	v_lshlrev_b32_e32 v52, 16, v40
	v_and_b32_e32 v53, 0xffff0000, v40
	s_waitcnt lgkmcnt(0)
	v_lshlrev_b32_e32 v48, 16, v44
	v_and_b32_e32 v49, 0xffff0000, v44
	v_pk_mul_f32 v[48:49], v[50:51], v[48:49]
	v_pk_add_f32 v[50:51], v[54:55], v[50:51] neg_lo:[0,1] neg_hi:[0,1]
	v_lshlrev_b32_e32 v44, 16, v45
	v_pk_fma_f32 v[48:49], v[50:51], v[52:53], v[48:49]
	v_and_b32_e32 v45, 0xffff0000, v45
	v_cvt_pk_bf16_f32 v32, v48, v49
	v_lshlrev_b32_e32 v36, 16, v37
	v_and_b32_e32 v37, 0xffff0000, v37
	v_lshlrev_b32_e32 v48, 16, v33
	v_and_b32_e32 v49, 0xffff0000, v33
	v_pk_mul_f32 v[44:45], v[36:37], v[44:45]
	v_lshlrev_b32_e32 v40, 16, v41
	v_and_b32_e32 v41, 0xffff0000, v41
	v_pk_add_f32 v[36:37], v[48:49], v[36:37] neg_lo:[0,1] neg_hi:[0,1]
	v_lshlrev_b32_e32 v48, 16, v34
	v_pk_fma_f32 v[36:37], v[36:37], v[40:41], v[44:45]
	v_lshlrev_b32_e32 v40, 16, v38
	v_cvt_pk_bf16_f32 v33, v36, v37
	v_lshlrev_b32_e32 v36, 16, v46
	v_and_b32_e32 v37, 0xffff0000, v46
	v_and_b32_e32 v41, 0xffff0000, v38
	v_and_b32_e32 v49, 0xffff0000, v34
	v_pk_mul_f32 v[36:37], v[40:41], v[36:37]
	v_lshlrev_b32_e32 v44, 16, v42
	v_and_b32_e32 v45, 0xffff0000, v42
	v_pk_add_f32 v[40:41], v[48:49], v[40:41] neg_lo:[0,1] neg_hi:[0,1]
	v_lshlrev_b32_e32 v38, 16, v39
	v_pk_fma_f32 v[36:37], v[40:41], v[44:45], v[36:37]
	v_and_b32_e32 v39, 0xffff0000, v39
	v_cvt_pk_bf16_f32 v34, v36, v37
	v_lshlrev_b32_e32 v36, 16, v47
	v_and_b32_e32 v37, 0xffff0000, v47
	v_lshlrev_b32_e32 v40, 16, v43
	v_and_b32_e32 v41, 0xffff0000, v43
	v_lshlrev_b32_e32 v42, 16, v35
	v_and_b32_e32 v43, 0xffff0000, v35
	v_pk_mul_f32 v[36:37], v[38:39], v[36:37]
	v_pk_add_f32 v[38:39], v[42:43], v[38:39] neg_lo:[0,1] neg_hi:[0,1]
	v_readlane_b32 s12, v255, 2
	v_pk_fma_f32 v[36:37], v[38:39], v[40:41], v[36:37]
	v_readlane_b32 s13, v255, 3
	v_cvt_pk_bf16_f32 v35, v36, v37
	s_waitcnt vmcnt(5)
	v_lshlrev_b32_e32 v38, 16, v24
	v_lshl_add_u64 v[36:37], s[12:13], 0, v[110:111]
	v_lshl_add_u64 v[36:37], v[36:37], 0, v[108:109]
	global_store_dwordx4 v[36:37], v[32:35], off
	ds_read_b128 v[32:35], v116 offset:6144
	v_and_b32_e32 v39, 0xffff0000, v24
	v_lshlrev_b32_e32 v42, 16, v20
	v_and_b32_e32 v43, 0xffff0000, v20
	s_waitcnt vmcnt(5)
	v_lshlrev_b32_e32 v40, 16, v28
	s_waitcnt lgkmcnt(0)
	v_lshlrev_b32_e32 v36, 16, v32
	v_and_b32_e32 v37, 0xffff0000, v32
	v_pk_mul_f32 v[36:37], v[38:39], v[36:37]
	v_and_b32_e32 v41, 0xffff0000, v28
	v_pk_add_f32 v[38:39], v[42:43], v[38:39] neg_lo:[0,1] neg_hi:[0,1]
	v_lshlrev_b32_e32 v32, 16, v33
	v_pk_fma_f32 v[36:37], v[38:39], v[40:41], v[36:37]
	v_and_b32_e32 v33, 0xffff0000, v33
	v_cvt_pk_bf16_f32 v20, v36, v37
	v_lshlrev_b32_e32 v24, 16, v25
	v_and_b32_e32 v25, 0xffff0000, v25
	v_lshlrev_b32_e32 v36, 16, v21
	v_and_b32_e32 v37, 0xffff0000, v21
	v_pk_mul_f32 v[32:33], v[24:25], v[32:33]
	v_lshlrev_b32_e32 v28, 16, v29
	v_and_b32_e32 v29, 0xffff0000, v29
	v_pk_add_f32 v[24:25], v[36:37], v[24:25] neg_lo:[0,1] neg_hi:[0,1]
	v_lshlrev_b32_e32 v36, 16, v22
	v_pk_fma_f32 v[24:25], v[24:25], v[28:29], v[32:33]
	v_lshlrev_b32_e32 v28, 16, v26
	v_cvt_pk_bf16_f32 v21, v24, v25
	v_lshlrev_b32_e32 v24, 16, v34
	v_and_b32_e32 v25, 0xffff0000, v34
	v_and_b32_e32 v29, 0xffff0000, v26
	v_and_b32_e32 v37, 0xffff0000, v22
	v_pk_mul_f32 v[24:25], v[28:29], v[24:25]
	v_lshlrev_b32_e32 v32, 16, v30
	v_and_b32_e32 v33, 0xffff0000, v30
	v_pk_add_f32 v[28:29], v[36:37], v[28:29] neg_lo:[0,1] neg_hi:[0,1]
	v_lshlrev_b32_e32 v26, 16, v27
	v_pk_fma_f32 v[24:25], v[28:29], v[32:33], v[24:25]
	v_and_b32_e32 v27, 0xffff0000, v27
	v_cvt_pk_bf16_f32 v22, v24, v25
	v_lshlrev_b32_e32 v24, 16, v35
	v_and_b32_e32 v25, 0xffff0000, v35
	v_lshlrev_b32_e32 v28, 16, v31
	v_and_b32_e32 v29, 0xffff0000, v31
	v_lshlrev_b32_e32 v30, 16, v23
	v_and_b32_e32 v31, 0xffff0000, v23
	v_pk_mul_f32 v[24:25], v[26:27], v[24:25]
	v_pk_add_f32 v[26:27], v[30:31], v[26:27] neg_lo:[0,1] neg_hi:[0,1]
	v_readlane_b32 s12, v255, 4
	v_pk_fma_f32 v[24:25], v[26:27], v[28:29], v[24:25]
	v_readlane_b32 s13, v255, 5
	v_cvt_pk_bf16_f32 v23, v24, v25
	s_waitcnt vmcnt(3)
	v_lshlrev_b32_e32 v26, 16, v12
	v_lshl_add_u64 v[24:25], s[12:13], 0, v[110:111]
	v_lshl_add_u64 v[24:25], v[24:25], 0, v[108:109]
	global_store_dwordx4 v[24:25], v[20:23], off
	ds_read_b128 v[20:23], v116 offset:7168
	v_and_b32_e32 v27, 0xffff0000, v12
	v_lshlrev_b32_e32 v30, 16, v8
	v_and_b32_e32 v31, 0xffff0000, v8
	s_waitcnt vmcnt(3)
	v_lshlrev_b32_e32 v28, 16, v16
	s_waitcnt lgkmcnt(0)
	v_lshlrev_b32_e32 v24, 16, v20
	v_and_b32_e32 v25, 0xffff0000, v20
	v_pk_mul_f32 v[24:25], v[26:27], v[24:25]
	v_and_b32_e32 v29, 0xffff0000, v16
	v_pk_add_f32 v[26:27], v[30:31], v[26:27] neg_lo:[0,1] neg_hi:[0,1]
	v_lshlrev_b32_e32 v20, 16, v21
	v_pk_fma_f32 v[24:25], v[26:27], v[28:29], v[24:25]
	v_and_b32_e32 v21, 0xffff0000, v21
	v_cvt_pk_bf16_f32 v8, v24, v25
	v_lshlrev_b32_e32 v12, 16, v13
	v_and_b32_e32 v13, 0xffff0000, v13
	v_lshlrev_b32_e32 v24, 16, v9
	v_and_b32_e32 v25, 0xffff0000, v9
	v_pk_mul_f32 v[20:21], v[12:13], v[20:21]
	v_lshlrev_b32_e32 v16, 16, v17
	v_and_b32_e32 v17, 0xffff0000, v17
	v_pk_add_f32 v[12:13], v[24:25], v[12:13] neg_lo:[0,1] neg_hi:[0,1]
	v_lshlrev_b32_e32 v24, 16, v10
	v_pk_fma_f32 v[12:13], v[12:13], v[16:17], v[20:21]
	v_lshlrev_b32_e32 v16, 16, v14
	v_cvt_pk_bf16_f32 v9, v12, v13
	v_lshlrev_b32_e32 v12, 16, v22
	v_and_b32_e32 v13, 0xffff0000, v22
	v_and_b32_e32 v17, 0xffff0000, v14
	v_and_b32_e32 v25, 0xffff0000, v10
	v_pk_mul_f32 v[12:13], v[16:17], v[12:13]
	v_lshlrev_b32_e32 v20, 16, v18
	v_and_b32_e32 v21, 0xffff0000, v18
	v_pk_add_f32 v[16:17], v[24:25], v[16:17] neg_lo:[0,1] neg_hi:[0,1]
	v_lshlrev_b32_e32 v14, 16, v15
	v_pk_fma_f32 v[12:13], v[16:17], v[20:21], v[12:13]
	v_and_b32_e32 v15, 0xffff0000, v15
	v_cvt_pk_bf16_f32 v10, v12, v13
	v_lshlrev_b32_e32 v12, 16, v23
	v_and_b32_e32 v13, 0xffff0000, v23
	v_lshlrev_b32_e32 v16, 16, v19
	v_and_b32_e32 v17, 0xffff0000, v19
	v_lshlrev_b32_e32 v18, 16, v11
	v_and_b32_e32 v19, 0xffff0000, v11
	v_pk_mul_f32 v[12:13], v[14:15], v[12:13]
	v_pk_add_f32 v[14:15], v[18:19], v[14:15] neg_lo:[0,1] neg_hi:[0,1]
	v_readlane_b32 s12, v255, 6
	v_pk_fma_f32 v[12:13], v[14:15], v[16:17], v[12:13]
	v_readlane_b32 s13, v255, 7
	v_cvt_pk_bf16_f32 v11, v12, v13
	s_nop 0
	v_lshl_add_u64 v[12:13], s[12:13], 0, v[110:111]
	v_lshl_add_u64 v[12:13], v[12:13], 0, v[108:109]
	global_store_dwordx4 v[12:13], v[8:11], off
	s_waitcnt lgkmcnt(0)
	s_waitcnt lgkmcnt(0)
	s_andn2_b64 vcc, exec, s[0:1]
	s_cbranch_vccnz .LBB0_503
	s_mov_b32 m0, s27
	v_lshl_add_u64 v[8:9], s[10:11], 0, v[4:5]
	global_load_lds_dwordx4 v[8:9], off
	v_lshl_add_u64 v[10:11], v[8:9], 0, s[62:63]
	s_mov_b32 m0, s53
	s_mov_b64 s[0:1], 0x20000
	global_load_lds_dwordx4 v[10:11], off
	v_lshl_add_u64 v[10:11], s[8:9], 0, v[0:1]
	s_mov_b32 m0, s26
	v_lshl_add_u64 v[12:13], v[10:11], 0, s[62:63]
	global_load_lds_dwordx4 v[10:11], off
	s_mov_b32 m0, s54
	s_nop 0
	global_load_lds_dwordx4 v[12:13], off
	v_lshl_add_u64 v[12:13], v[8:9], 0, s[44:45]
	s_mov_b32 m0, s55
	v_lshl_add_u64 v[8:9], v[8:9], 0, s[46:47]
	global_load_lds_dwordx4 v[12:13], off
	s_mov_b32 m0, s57
	s_nop 0
	global_load_lds_dwordx4 v[8:9], off
	v_lshl_add_u64 v[8:9], v[10:11], 0, s[0:1]
	s_mov_b32 m0, s58
	s_nop 0
	global_load_lds_dwordx4 v[8:9], off
	v_lshl_add_u64 v[8:9], v[10:11], 0, s[48:49]
	s_mov_b32 m0, s59
	s_nop 0
	global_load_lds_dwordx4 v[8:9], off
	s_branch .LBB0_503
